# v23 + GEMM k-loops: per-phase s_setprio flips deleted, one static s_setprio 1 for waves 0-3 during each unit's k-loop (cleared at loop exit)
# baseline (speedup 1.0000x reference)
.LBB0_211:
	s_cmp_lt_u32 s53, 0x1000
	s_cbranch_scc0 .Lprio_done_3
	s_setprio 1

.LBB0_395:
	s_cmp_lt_u32 s60, 0x1000
	s_cbranch_scc0 .Lprio_done_0
	s_setprio 1

.LBB0_1098:
	s_cmp_lt_u32 s69, 0x1000
	s_cbranch_scc0 .Lprio_done_2
	s_setprio 1

.LBB0_1174:
	s_cmp_lt_u32 s79, 0x1000
	s_cbranch_scc0 .Lprio_done_1
	s_setprio 1
